# attention PV phase: counted lgkmcnt waits per MFMA instead of lgkmcnt(0) at each d0-group boundary
# speedup vs baseline: 1.0057x; 1.0037x over previous
; __device__ __forceinline__ void finishSM(f32x16& p0, f32x16& p1, float alpha, float& l_reg, bf16x8& pa0, bf16x8& pa1, bf16x8& pa2, bf16x8& pa3) {
; #pragma unroll
;   for (int r = 0; r < 16; ++r) p1[r] = __builtin_amdgcn_exp2f(p1[r]);
;   float ps = 0;
; #pragma unroll
;   for (int r = 0; r < 16; ++r) ps += p0[r];
; #pragma unroll
;   for (int r = 0; r < 16; ++r) ps += p1[r];
;   { auto rr = __builtin_amdgcn_permlane32_swap(__float_as_uint(ps), __float_as_uint(ps), false, false);
;     ps = __uint_as_float(rr[0]) + __uint_as_float(rr[1]); }
;   l_reg = l_reg * alpha + ps;
; template <bool MLA>
; __device__ __forceinline__ void qkt(f32x16& p0, f32x16& p1, const char* Ks, const char* KRs, const bf16x8* qr, const char* qrl, const f32x16& negm, int r32, int hi) {
; #pragma unroll
;   for (int d0 = 0; d0 < 8; ++d0) { int cb = (d0 * 16 + hi * 8) * 2;
;     bf16x8 b0 = *reinterpret_cast<const bf16x8*>(Ks + KSWZ(r32, cb));
;     bf16x8 b1 = *reinterpret_cast<const bf16x8*>(Ks + KSWZ(32 + r32, cb));
;     if (d0 == 0) { p0 = __builtin_amdgcn_mfma_f32_32x32x16_bf16(b0, qr[0], negm, 0, 0, 0); p1 = __builtin_amdgcn_mfma_f32_32x32x16_bf16(b1, qr[0], negm, 0, 0, 0); }
;     else { p0 = __builtin_amdgcn_mfma_f32_32x32x16_bf16(b0, qr[d0], p0, 0, 0, 0); p1 = __builtin_amdgcn_mfma_f32_32x32x16_bf16(b1, qr[d0], p1, 0, 0, 0); } }
;   if constexpr (MLA) {
; #pragma unroll
;     for (int d0 = 0; d0 < 4; ++d0) { int ch = d0 * 2 + hi;
;       bf16x8 b0 = *reinterpret_cast<const bf16x8*>(KRs + KRSWZ(r32, ch));
;       bf16x8 b1 = *reinterpret_cast<const bf16x8*>(KRs + KRSWZ(32 + r32, ch));
;       const bf16x8 qq = *reinterpret_cast<const bf16x8*>(qrl + d0 * 1024);
;       p0 = __builtin_amdgcn_mfma_f32_32x32x16_bf16(b0, qq, p0, 0, 0, 0);
;       p1 = __builtin_amdgcn_mfma_f32_32x32x16_bf16(b1, qq, p1, 0, 0, 0); }
;   }
.LBB0_101:
	s_mov_b32 s10, s24
	s_mov_b32 s24, s35
	s_lshl_b32 s2, s25, 14
	s_add_i32 s27, s2, 0
	s_add_i32 s32, s27, s15
	s_lshl_b32 s30, s25, 13
	s_lshl_b32 s11, s10, 14
	s_add_i32 s3, s11, 0
	v_add_u32_e32 v0, s3, v210
	ds_read_b128 v[234:237], v0 offset:57344
	ds_read_b128 v[98:101], v0 offset:49152
	v_add_u32_e32 v0, s3, v209
	s_lshl_b32 s2, s10, 13
	s_add_i32 s2, s2, 0
	s_add_i32 s2, s2, 0x18000
	s_add_u32 vcc_lo, s28, s46
	s_addc_u32 vcc_hi, s29, s47
	s_add_i32 m0, s32, 0xc000
	v_lshl_add_u64 v[250:251], v[172:173], 0, vcc
	global_load_lds_dwordx4 v[250:251], off
	v_exp_f32_e32 v213, v82
	v_add_f32_e32 v212, 0, v227
	v_add_f32_e32 v212, v229, v212
	s_waitcnt lgkmcnt(0)
	v_mfma_f32_32x32x16_bf16 v[114:129], v[98:101], v[158:161], v[66:81]
	v_exp_f32_e32 v246, v83
	v_add_f32_e32 v212, v225, v212
	v_add_f32_e32 v212, v228, v212
	s_lshl_b32 s31, s35, 14
	v_mfma_f32_32x32x16_bf16 v[98:113], v[234:237], v[158:161], v[66:81]
	ds_read_b128 v[234:237], v0 offset:57344
	ds_read_b128 v[238:241], v0 offset:49152
	v_add_u32_e32 v0, s3, v208
	s_add_u32 vcc_lo, s28, 0x4380100
	s_addc_u32 vcc_hi, s29, 0
	s_mov_b32 m0, s32
	v_lshl_add_u64 v[250:251], v[170:171], 0, vcc
	global_load_lds_dwordx4 v[250:251], off
	v_exp_f32_e32 v247, v84
	v_add_f32_e32 v212, v224, v212
	v_add_f32_e32 v212, v226, v212
	s_waitcnt lgkmcnt(0)
	v_mfma_f32_32x32x16_bf16 v[114:129], v[238:241], v[154:157], v[114:129]
	v_exp_f32_e32 v249, v85
	v_add_f32_e32 v212, v222, v212
	v_add_f32_e32 v212, v223, v212
	v_mfma_f32_32x32x16_bf16 v[98:113], v[234:237], v[154:157], v[98:113]
	ds_read_b128 v[234:237], v0 offset:57344
	ds_read_b128 v[238:241], v0 offset:49152
	v_add_u32_e32 v0, s3, v207
	s_add_u32 vcc_lo, s28, s46
	s_addc_u32 vcc_hi, s29, s47
	s_add_i32 m0, s32, 0xc400
	v_lshl_add_u64 v[250:251], v[174:175], 0, vcc
	global_load_lds_dwordx4 v[250:251], off
	v_exp_f32_e32 v252, v86
	v_add_f32_e32 v212, v219, v212
	v_add_f32_e32 v212, v221, v212
	s_waitcnt lgkmcnt(0)
	v_mfma_f32_32x32x16_bf16 v[114:129], v[238:241], v[150:153], v[114:129]
	v_exp_f32_e32 v253, v87
	v_add_f32_e32 v212, v218, v212
	v_add_f32_e32 v212, v220, v212
	v_mfma_f32_32x32x16_bf16 v[98:113], v[234:237], v[150:153], v[98:113]
	ds_read_b128 v[234:237], v0 offset:57344
	ds_read_b128 v[238:241], v0 offset:49152
	v_add_u32_e32 v0, s3, v206
	s_add_u32 vcc_lo, s28, 0x4380180
	s_addc_u32 vcc_hi, s29, 0
	s_add_i32 m0, s32, 0x400
	v_lshl_add_u64 v[250:251], v[170:171], 0, vcc
	global_load_lds_dwordx4 v[250:251], off
	v_exp_f32_e32 v254, v88
	v_add_f32_e32 v212, v215, v212
	v_add_f32_e32 v212, v217, v212
	s_waitcnt lgkmcnt(0)
	v_mfma_f32_32x32x16_bf16 v[114:129], v[238:241], v[146:149], v[114:129]
	v_exp_f32_e32 v255, v89
	v_add_f32_e32 v212, v214, v212
	v_add_f32_e32 v212, v216, v212
	v_mfma_f32_32x32x16_bf16 v[98:113], v[234:237], v[146:149], v[98:113]
	ds_read_b128 v[234:237], v0 offset:57344
	ds_read_b128 v[238:241], v0 offset:49152
	v_add_u32_e32 v0, s3, v205
	s_add_u32 vcc_lo, s28, 0x2e340600
	s_addc_u32 vcc_hi, s29, 0
	s_add_i32 m0, s23, s30
	v_lshl_add_u64 v[250:251], v[168:169], 0, vcc
	global_load_lds_dwordx4 v[250:251], off
	v_cvt_pk_bf16_f32 v82, v227, v229
	v_exp_f32_e32 v90, v90
	v_cvt_pk_bf16_f32 v83, v225, v228
	s_waitcnt lgkmcnt(0)
	v_mfma_f32_32x32x16_bf16 v[114:129], v[238:241], v[142:145], v[114:129]
	v_exp_f32_e32 v91, v91
	v_cvt_pk_bf16_f32 v84, v224, v226
	v_exp_f32_e32 v92, v92
	v_mfma_f32_32x32x16_bf16 v[98:113], v[234:237], v[142:145], v[98:113]
	ds_read_b128 v[234:237], v0 offset:57344
	ds_read_b128 v[238:241], v0 offset:49152
	v_add_u32_e32 v0, s3, v204
	v_cvt_pk_bf16_f32 v85, v222, v223
	v_exp_f32_e32 v93, v93
	v_cvt_pk_bf16_f32 v86, v219, v221
	s_waitcnt lgkmcnt(0)
	v_mfma_f32_32x32x16_bf16 v[114:129], v[238:241], v[138:141], v[114:129]
	v_exp_f32_e32 v94, v94
	v_cvt_pk_bf16_f32 v87, v218, v220
	v_exp_f32_e32 v95, v95
	v_mfma_f32_32x32x16_bf16 v[98:113], v[234:237], v[138:141], v[98:113]
	ds_read_b128 v[234:237], v0 offset:57344
	ds_read_b128 v[238:241], v0 offset:49152
	v_add_u32_e32 v0, s3, v203
	v_cvt_pk_bf16_f32 v88, v215, v217
	v_exp_f32_e32 v96, v96
	v_cvt_pk_bf16_f32 v89, v214, v216
	s_waitcnt lgkmcnt(0)
	v_mfma_f32_32x32x16_bf16 v[114:129], v[238:241], v[134:137], v[114:129]
	v_exp_f32_e32 v97, v97
	v_add_f32_e32 v212, v213, v212
	v_add_f32_e32 v212, v246, v212
	v_mfma_f32_32x32x16_bf16 v[98:113], v[234:237], v[134:137], v[98:113]
	ds_read_b128 v[234:237], v0 offset:57344
	ds_read_b128 v[238:241], v0 offset:49152
	v_add_u32_e32 v0, s2, v200
	v_add_f32_e32 v212, v247, v212
	v_add_f32_e32 v212, v249, v212
	v_add_f32_e32 v212, v252, v212
	s_waitcnt lgkmcnt(0)
	v_mfma_f32_32x32x16_bf16 v[114:129], v[238:241], v[130:133], v[114:129]
	v_add_f32_e32 v212, v253, v212
	v_add_f32_e32 v212, v254, v212
	v_add_f32_e32 v212, v255, v212
	v_mfma_f32_32x32x16_bf16 v[98:113], v[234:237], v[130:133], v[98:113]
	ds_read_b128 v[234:237], v0
	ds_read_b128 v[238:241], v0 offset:4096
	ds_read_b128 v[242:245], v198
	v_add_u32_e32 v0, s2, v201
	v_add_f32_e32 v212, v90, v212
	v_add_f32_e32 v212, v91, v212
	s_waitcnt lgkmcnt(0)
	v_mfma_f32_32x32x16_bf16 v[114:129], v[234:237], v[242:245], v[114:129]
	v_add_f32_e32 v212, v92, v212
	v_add_f32_e32 v212, v93, v212
	v_mfma_f32_32x32x16_bf16 v[98:113], v[238:241], v[242:245], v[98:113]
	ds_read_b128 v[234:237], v0
	ds_read_b128 v[238:241], v0 offset:4096
	ds_read_b128 v[242:245], v198 offset:1024
	v_add_u32_e32 v0, s2, v199
	v_add_f32_e32 v212, v94, v212
	v_add_f32_e32 v212, v95, v212
	s_waitcnt lgkmcnt(0)
; #define SBAR() __builtin_amdgcn_sched_barrier(0)
; __device__ __forceinline__ float max3f(float a, float b, float c) { return __builtin_fmaxf(__builtin_fmaxf(a, b), c); }
; template <bool FIRST, bool MLA>
; __device__ __forceinline__ void partialSM(f32x16& p0, f32x16& p1, f32x16& negm, float& m_reg, float& alpha) {
;   float a = max3f(p0[0], p0[1], p1[0]), b = max3f(p0[2], p0[3], p1[1]); a = max3f(a, p1[2], p1[3]);
; #pragma unroll
;   for (int r = 4; r < 16; r += 4) { a = max3f(a, p0[r], p0[r + 1]); b = max3f(b, p0[r + 2], p0[r + 3]); a = max3f(a, p1[r], p1[r + 1]); b = max3f(b, p1[r + 2], p1[r + 3]); }
;   float pmax = fmaxf(a, b);
;   { auto rr = __builtin_amdgcn_permlane32_swap(__float_as_uint(pmax), __float_as_uint(pmax), false, false);
;     pmax = fmaxf(__uint_as_float(rr[0]), __uint_as_float(rr[1])); }
;   alpha = 1.f;
;   if constexpr (MLA) {
;     if (FIRST) m_reg = pmax;
;     else if (!__builtin_expect(__all(pmax - m_reg <= THR2), 1)) { const float mn = fmaxf(m_reg, pmax); alpha = __builtin_amdgcn_exp2f(m_reg - mn); m_reg = mn; }
; #pragma unroll
;     for (int r = 0; r < 16; ++r) { p0[r] -= m_reg; p1[r] -= m_reg; }
;   } else
;   if (FIRST || __builtin_expect(__any(pmax > THR2), 0)) {
; template <int D0> __device__ __forceinline__ void pv_one(f32x16& od, int vb, bf16x8 pa0, bf16x8 pa1, bf16x8 pa2, bf16x8 pa3) {
;   const s16x4 l0 = tr_read<v_rd_off(D0, 0, 0)>(vb), h0 = tr_read<v_rd_off(D0, 0, 1)>(vb), l1 = tr_read<v_rd_off(D0, 1, 0)>(vb), h1 = tr_read<v_rd_off(D0, 1, 1)>(vb);
;   const s16x4 l2 = tr_read<v_rd_off(D0, 2, 0)>(vb), h2 = tr_read<v_rd_off(D0, 2, 1)>(vb), l3 = tr_read<v_rd_off(D0, 3, 0)>(vb), h3 = tr_read<v_rd_off(D0, 3, 1)>(vb);
;   asm volatile("s_waitcnt lgkmcnt(0)" ::: "memory"); SBAR();
;     ...
;   od = __builtin_amdgcn_mfma_f32_32x32x16_bf16(pa0, PK(l0, h0), od, 0, 0, 0);
;   od = __builtin_amdgcn_mfma_f32_32x32x16_bf16(pa1, PK(l1, h1), od, 0, 0, 0);
;   od = __builtin_amdgcn_mfma_f32_32x32x16_bf16(pa2, PK(l2, h2), od, 0, 0, 0);
;   od = __builtin_amdgcn_mfma_f32_32x32x16_bf16(pa3, PK(l3, h3), od, 0, 0, 0);
;     ...
; }
; __device__ __forceinline__ void pv_d0(f32x16* o, int vb, bf16x8 pa0, bf16x8 pa1, bf16x8 pa2, bf16x8 pa3) {
;   pv_one<0>(o[0], vb, pa0, pa1, pa2, pa3); pv_one<1>(o[1], vb, pa0, pa1, pa2, pa3); pv_one<2>(o[2], vb, pa0, pa1, pa2, pa3); pv_one<3>(o[3], vb, pa0, pa1, pa2, pa3);
	v_mfma_f32_32x32x16_bf16 v[114:129], v[234:237], v[242:245], v[114:129]
	v_add_f32_e32 v212, v96, v212
	v_add_f32_e32 v212, v97, v212
	v_mfma_f32_32x32x16_bf16 v[98:113], v[238:241], v[242:245], v[98:113]
	ds_read_b128 v[234:237], v0
	ds_read_b128 v[238:241], v0 offset:4096
	ds_read_b128 v[242:245], v198 offset:2048
	v_add_u32_e32 v0, s2, v202
	v_cvt_pk_bf16_f32 v97, v96, v97
	v_cvt_pk_bf16_f32 v96, v94, v95
	s_waitcnt lgkmcnt(0)
	v_mfma_f32_32x32x16_bf16 v[114:129], v[234:237], v[242:245], v[114:129]
	v_cvt_pk_bf16_f32 v95, v92, v93
	v_cvt_pk_bf16_f32 v94, v90, v91
	v_mfma_f32_32x32x16_bf16 v[98:113], v[238:241], v[242:245], v[98:113]
	ds_read_b128 v[234:237], v0
	ds_read_b128 v[238:241], v0 offset:4096
	ds_read_b128 v[242:245], v198 offset:3072
	v_cvt_pk_bf16_f32 v90, v213, v246
	v_cvt_pk_bf16_f32 v91, v247, v249
	s_waitcnt lgkmcnt(0)
	v_mfma_f32_32x32x16_bf16 v[114:129], v[234:237], v[242:245], v[114:129]
	v_cvt_pk_bf16_f32 v92, v252, v253
	v_cvt_pk_bf16_f32 v93, v254, v255
	v_mfma_f32_32x32x16_bf16 v[98:113], v[238:241], v[242:245], v[98:113]
	v_add_u32_e32 v213, s31, v197
	ds_read_b64_tr_b16 v[214:215], v213 offset:0
	ds_read_b64_tr_b16 v[216:217], v213 offset:0x800
	ds_read_b64_tr_b16 v[218:219], v213 offset:0x1000
	ds_read_b64_tr_b16 v[220:221], v213 offset:0x1800
	ds_read_b64_tr_b16 v[222:223], v213 offset:0x2000
	ds_read_b64_tr_b16 v[224:225], v213 offset:0x2800
	ds_read_b64_tr_b16 v[226:227], v213 offset:0x3000
	ds_read_b64_tr_b16 v[228:229], v213 offset:0x3800
	s_waitcnt lgkmcnt(0)
	v_mov_b32_e32 v0, v212
	s_nop 1
	v_permlane32_swap_b32_e32 v0, v212
	v_permlane32_swap_b32_e32 v82, v84
	v_permlane32_swap_b32_e32 v83, v85
	v_permlane32_swap_b32_e32 v86, v88
	v_permlane32_swap_b32_e32 v87, v89
	v_permlane32_swap_b32_e32 v90, v92
	v_permlane32_swap_b32_e32 v91, v93
	v_permlane32_swap_b32_e32 v94, v96
	v_permlane32_swap_b32_e32 v95, v97
	v_mfma_f32_32x32x16_bf16 v[50:65], v[82:85], v[214:217], v[50:65]
	ds_read_b64_tr_b16 v[214:215], v213 offset:0x200
	ds_read_b64_tr_b16 v[216:217], v213 offset:0xa00
	v_mfma_f32_32x32x16_bf16 v[50:65], v[86:89], v[218:221], v[50:65]
	ds_read_b64_tr_b16 v[218:219], v213 offset:0x1200
	ds_read_b64_tr_b16 v[220:221], v213 offset:0x1a00
	v_mfma_f32_32x32x16_bf16 v[50:65], v[90:93], v[222:225], v[50:65]
	ds_read_b64_tr_b16 v[222:223], v213 offset:0x2200
	ds_read_b64_tr_b16 v[224:225], v213 offset:0x2a00
	v_mfma_f32_32x32x16_bf16 v[50:65], v[94:97], v[226:229], v[50:65]
	ds_read_b64_tr_b16 v[226:227], v213 offset:0x3200
	ds_read_b64_tr_b16 v[228:229], v213 offset:0x3a00
	s_waitcnt lgkmcnt(6)
	v_mfma_f32_32x32x16_bf16 v[34:49], v[82:85], v[214:217], v[34:49]
	ds_read_b64_tr_b16 v[214:215], v213 offset:0x400
	ds_read_b64_tr_b16 v[216:217], v213 offset:0xc00
	s_waitcnt lgkmcnt(6)
	v_mfma_f32_32x32x16_bf16 v[34:49], v[86:89], v[218:221], v[34:49]
	ds_read_b64_tr_b16 v[218:219], v213 offset:0x1400
	ds_read_b64_tr_b16 v[220:221], v213 offset:0x1c00
	s_waitcnt lgkmcnt(6)
	v_mfma_f32_32x32x16_bf16 v[34:49], v[90:93], v[222:225], v[34:49]
	ds_read_b64_tr_b16 v[222:223], v213 offset:0x2400
	ds_read_b64_tr_b16 v[224:225], v213 offset:0x2c00
	s_waitcnt lgkmcnt(6)
	v_mfma_f32_32x32x16_bf16 v[34:49], v[94:97], v[226:229], v[34:49]
	ds_read_b64_tr_b16 v[226:227], v213 offset:0x3400
	ds_read_b64_tr_b16 v[228:229], v213 offset:0x3c00
	s_waitcnt lgkmcnt(6)
	v_mfma_f32_32x32x16_bf16 v[18:33], v[82:85], v[214:217], v[18:33]
	ds_read_b64_tr_b16 v[214:215], v213 offset:0x600
	ds_read_b64_tr_b16 v[216:217], v213 offset:0xe00
	s_waitcnt lgkmcnt(6)
	v_mfma_f32_32x32x16_bf16 v[18:33], v[86:89], v[218:221], v[18:33]
	ds_read_b64_tr_b16 v[218:219], v213 offset:0x1600
	ds_read_b64_tr_b16 v[220:221], v213 offset:0x1e00
	s_waitcnt lgkmcnt(6)
	v_mfma_f32_32x32x16_bf16 v[18:33], v[90:93], v[222:225], v[18:33]
	ds_read_b64_tr_b16 v[222:223], v213 offset:0x2600
	ds_read_b64_tr_b16 v[224:225], v213 offset:0x2e00
	s_waitcnt lgkmcnt(6)
	v_mfma_f32_32x32x16_bf16 v[18:33], v[94:97], v[226:229], v[18:33]
	ds_read_b64_tr_b16 v[226:227], v213 offset:0x3600
	ds_read_b64_tr_b16 v[228:229], v213 offset:0x3e00
	s_waitcnt lgkmcnt(6)
	v_mfma_f32_32x32x16_bf16 v[2:17], v[82:85], v[214:217], v[2:17]
	v_max_f32_e32 v82, v115, v115
	v_max_f32_e32 v83, v114, v114
	v_max_f32_e32 v82, v83, v82
	v_max3_f32 v83, v116, v117, v99
	v_max3_f32 v82, v82, v98, v100
	v_max3_f32 v82, v82, v101, v118
	v_max3_f32 v83, v83, v120, v121
	s_waitcnt lgkmcnt(4)
	v_mfma_f32_32x32x16_bf16 v[2:17], v[86:89], v[218:221], v[2:17]
	v_max3_f32 v82, v82, v119, v102
	v_max3_f32 v83, v83, v104, v105
	v_max3_f32 v82, v82, v103, v122
	v_max3_f32 v83, v83, v124, v125
	v_max3_f32 v82, v82, v123, v106
	v_max3_f32 v83, v83, v108, v109
	v_max3_f32 v82, v82, v107, v126
	s_waitcnt lgkmcnt(2)
	v_mfma_f32_32x32x16_bf16 v[2:17], v[90:93], v[222:225], v[2:17]
	v_max3_f32 v83, v83, v128, v129
	v_max3_f32 v82, v82, v127, v110
	v_max3_f32 v83, v83, v112, v113
	v_max3_f32 v82, v82, v111, v83
	v_mov_b32_e32 v83, v82
	s_nop 1
	v_permlane32_swap_b32_e32 v82, v83
	s_waitcnt lgkmcnt(0)
	v_mfma_f32_32x32x16_bf16 v[2:17], v[94:97], v[226:229], v[2:17]
	v_max_f32_e32 v83, v83, v83
	v_max_f32_e32 v82, v82, v82
	v_max_f32_e32 v82, v82, v83
	v_cmp_lt_f32_e32 vcc, s40, v82
	s_cbranch_vccnz .LBB0_113
	v_mov_b32_e32 v213, 1.0
	v_cmp_gt_f32_e32 vcc, 1.0, v213
	s_cbranch_vccz .LBB0_106

; #define SBAR() __builtin_amdgcn_sched_barrier(0)
; #define WAIT_BAR() do { asm volatile("s_waitcnt vmcnt(0)" ::: "memory"); __syncthreads(); } while (0)
; #define RESC(a) do { if (__any((a) < 1.f)) { if (hi == 0) al_l[r32] = (a); asm volatile("s_waitcnt lgkmcnt(0)" ::: "memory"); \
;     _Pragma("unroll") for (int d = 0; d < 4; ++d) _Pragma("unroll") for (int r = 0; r < 16; ++r) o[d][r] *= al_l[crow(r, hi)]; } } while (0)
; #define ROT() do { const int t_ = s_prev; s_prev = s_cur; s_cur = s_next; s_next = t_; } while (0)
; template <bool MLA>
; __device__ __forceinline__ void qkt(f32x16& p0, f32x16& p1, const char* Ks, const char* KRs, const bf16x8* qr, const char* qrl, const f32x16& negm, int r32, int hi) {
; #pragma unroll
;   for (int d0 = 0; d0 < 8; ++d0) { int cb = (d0 * 16 + hi * 8) * 2;
;     bf16x8 b0 = *reinterpret_cast<const bf16x8*>(Ks + KSWZ(r32, cb));
;     bf16x8 b1 = *reinterpret_cast<const bf16x8*>(Ks + KSWZ(32 + r32, cb));
;     if (d0 == 0) { p0 = __builtin_amdgcn_mfma_f32_32x32x16_bf16(b0, qr[0], negm, 0, 0, 0); p1 = __builtin_amdgcn_mfma_f32_32x32x16_bf16(b1, qr[0], negm, 0, 0, 0); }
;     else { p0 = __builtin_amdgcn_mfma_f32_32x32x16_bf16(b0, qr[d0], p0, 0, 0, 0); p1 = __builtin_amdgcn_mfma_f32_32x32x16_bf16(b1, qr[d0], p1, 0, 0, 0); } }
;   if constexpr (MLA) {
; #pragma unroll
;     for (int d0 = 0; d0 < 4; ++d0) { int ch = d0 * 2 + hi;
;       bf16x8 b0 = *reinterpret_cast<const bf16x8*>(KRs + KRSWZ(r32, ch));
;       bf16x8 b1 = *reinterpret_cast<const bf16x8*>(KRs + KRSWZ(32 + r32, ch));
;       const bf16x8 qq = *reinterpret_cast<const bf16x8*>(qrl + d0 * 1024);
;       p0 = __builtin_amdgcn_mfma_f32_32x32x16_bf16(b0, qq, p0, 0, 0, 0);
;       p1 = __builtin_amdgcn_mfma_f32_32x32x16_bf16(b1, qq, p1, 0, 0, 0); }
;   }
; template <bool MLA> ...
;     ...
;     RESC(alB); WAIT_BAR(); ROT();
;     SBAR(); DMA_TILE(j + 2, s_next); SBAR();
;     qkt<MLA>(pA0, pA1, K_lds + s_cur * SHM_K, KR_lds + s_cur * SHM_KR, qr, qrl, negm, r32, hi);
;     finishSM(pB0, pB1, alB, l_reg, pa0, pa1, pa2, pa3);
;     pv_d0(o, vb0 + s_prev * SHM_V, pa0, pa1, pa2, pa3); partialSM<false, false>(pA0, pA1, negm, m_reg, alA);
;     RESC(alA); WAIT_BAR(); ROT();
.LBB0_106:
	s_waitcnt vmcnt(0)
	v_exp_f32_e32 v218, v114
	v_exp_f32_e32 v219, v115
	v_exp_f32_e32 v220, v116
	v_exp_f32_e32 v221, v117
	v_exp_f32_e32 v222, v118
	v_exp_f32_e32 v223, v119
	v_exp_f32_e32 v224, v120
	v_exp_f32_e32 v225, v121
	v_exp_f32_e32 v226, v122
	v_exp_f32_e32 v227, v123
	v_exp_f32_e32 v228, v124
	v_exp_f32_e32 v229, v125
	v_exp_f32_e32 v234, v126
	v_exp_f32_e32 v235, v127
	v_exp_f32_e32 v236, v128
	v_exp_f32_e32 v237, v129
	s_waitcnt vmcnt(0)
	s_barrier
	s_add_i32 s31, s19, s31
	v_add_u32_e32 v82, s27, v210
	ds_read_b128 v[176:179], v82 offset:57344
	ds_read_b128 v[82:85], v82 offset:49152
	v_add_u32_e32 v180, s27, v209
	s_add_i32 s2, s30, 0
	s_add_i32 s2, s2, 0x18000
	s_add_u32 vcc_lo, s28, s48
	s_addc_u32 vcc_hi, s29, s49
	s_add_i32 m0, s31, 0xc000
	v_lshl_add_u64 v[250:251], v[172:173], 0, vcc
	global_load_lds_dwordx4 v[250:251], off
	v_exp_f32_e32 v238, v100
	v_add_f32_e32 v255, 0, v218
	v_add_f32_e32 v255, v219, v255
	s_waitcnt lgkmcnt(0)
	v_mfma_f32_32x32x16_bf16 v[114:129], v[82:85], v[158:161], v[66:81]
	v_exp_f32_e32 v239, v101
	v_add_f32_e32 v255, v220, v255
	v_add_f32_e32 v255, v221, v255
	v_mfma_f32_32x32x16_bf16 v[82:97], v[176:179], v[158:161], v[66:81]
	ds_read_b128 v[176:179], v180 offset:57344
	ds_read_b128 v[180:183], v180 offset:49152
	s_add_u32 vcc_lo, s28, 0x43c0100
	s_addc_u32 vcc_hi, s29, 0
	s_mov_b32 m0, s31
	v_lshl_add_u64 v[250:251], v[170:171], 0, vcc
	global_load_lds_dwordx4 v[250:251], off
	v_exp_f32_e32 v246, v102
	v_add_f32_e32 v255, v222, v255
	v_add_f32_e32 v255, v223, v255
	s_waitcnt lgkmcnt(0)
	v_mfma_f32_32x32x16_bf16 v[114:129], v[180:183], v[154:157], v[114:129]
	v_exp_f32_e32 v247, v103
	v_add_f32_e32 v255, v224, v255
	v_add_f32_e32 v255, v225, v255
	v_add_u32_e32 v180, s27, v208
	v_mfma_f32_32x32x16_bf16 v[82:97], v[176:179], v[154:157], v[82:97]
	ds_read_b128 v[176:179], v180 offset:57344
	ds_read_b128 v[180:183], v180 offset:49152
	s_add_u32 vcc_lo, s28, s48
	s_addc_u32 vcc_hi, s29, s49
	s_add_i32 m0, s31, 0xc400
	v_lshl_add_u64 v[250:251], v[174:175], 0, vcc
	global_load_lds_dwordx4 v[250:251], off
	v_exp_f32_e32 v249, v104
	v_add_f32_e32 v255, v226, v255
	v_add_f32_e32 v255, v227, v255
	s_waitcnt lgkmcnt(0)
	v_mfma_f32_32x32x16_bf16 v[114:129], v[180:183], v[150:153], v[114:129]
	v_exp_f32_e32 v252, v105
	v_add_f32_e32 v255, v228, v255
	v_add_f32_e32 v255, v229, v255
	v_add_u32_e32 v180, s27, v207
	v_mfma_f32_32x32x16_bf16 v[82:97], v[176:179], v[150:153], v[82:97]
	ds_read_b128 v[176:179], v180 offset:57344
	ds_read_b128 v[180:183], v180 offset:49152
	s_add_u32 vcc_lo, s28, 0x43c0180
	s_addc_u32 vcc_hi, s29, 0
	s_add_i32 m0, s31, 0x400
	v_lshl_add_u64 v[250:251], v[170:171], 0, vcc
	global_load_lds_dwordx4 v[250:251], off
	v_exp_f32_e32 v253, v106
	v_add_f32_e32 v255, v234, v255
	v_add_f32_e32 v255, v235, v255
	s_waitcnt lgkmcnt(0)
	v_mfma_f32_32x32x16_bf16 v[114:129], v[180:183], v[146:149], v[114:129]
	v_exp_f32_e32 v254, v107
	v_add_f32_e32 v255, v236, v255
	v_add_f32_e32 v255, v237, v255
	v_add_u32_e32 v180, s27, v206
	v_mfma_f32_32x32x16_bf16 v[82:97], v[176:179], v[146:149], v[82:97]
	ds_read_b128 v[176:179], v180 offset:57344
	ds_read_b128 v[180:183], v180 offset:49152
	s_lshl_b32 s32, s24, 13
	s_add_u32 vcc_lo, s28, 0x2e360600
	s_addc_u32 vcc_hi, s29, 0
	s_add_i32 m0, s23, s32
	v_lshl_add_u64 v[250:251], v[168:169], 0, vcc
	global_load_lds_dwordx4 v[250:251], off
	v_cvt_pk_bf16_f32 v100, v218, v219
	v_exp_f32_e32 v98, v98
	s_waitcnt lgkmcnt(0)
	v_mfma_f32_32x32x16_bf16 v[114:129], v[180:183], v[142:145], v[114:129]
	v_cvt_pk_bf16_f32 v101, v220, v221
	v_exp_f32_e32 v99, v99
	v_add_u32_e32 v180, s27, v205
	v_mfma_f32_32x32x16_bf16 v[82:97], v[176:179], v[142:145], v[82:97]
	ds_read_b128 v[176:179], v180 offset:57344
	ds_read_b128 v[180:183], v180 offset:49152
	v_cvt_pk_bf16_f32 v102, v222, v223
	v_exp_f32_e32 v108, v108
	s_waitcnt lgkmcnt(0)
	v_mfma_f32_32x32x16_bf16 v[114:129], v[180:183], v[138:141], v[114:129]
	v_cvt_pk_bf16_f32 v103, v224, v225
	v_exp_f32_e32 v109, v109
	v_add_u32_e32 v180, s27, v204
	v_mfma_f32_32x32x16_bf16 v[82:97], v[176:179], v[138:141], v[82:97]
	ds_read_b128 v[176:179], v180 offset:57344
	ds_read_b128 v[180:183], v180 offset:49152
	v_cvt_pk_bf16_f32 v104, v226, v227
	v_exp_f32_e32 v110, v110
	s_waitcnt lgkmcnt(0)
	v_mfma_f32_32x32x16_bf16 v[114:129], v[180:183], v[134:137], v[114:129]
	v_cvt_pk_bf16_f32 v105, v228, v229
	v_exp_f32_e32 v111, v111
	v_add_u32_e32 v180, s27, v203
	v_mfma_f32_32x32x16_bf16 v[82:97], v[176:179], v[134:137], v[82:97]
	ds_read_b128 v[176:179], v180 offset:57344
	ds_read_b128 v[180:183], v180 offset:49152
	v_cvt_pk_bf16_f32 v106, v234, v235
	v_exp_f32_e32 v112, v112
	s_waitcnt lgkmcnt(0)
	v_mfma_f32_32x32x16_bf16 v[114:129], v[180:183], v[130:133], v[114:129]
	v_cvt_pk_bf16_f32 v107, v236, v237
	v_exp_f32_e32 v113, v113
	v_add_u32_e32 v180, s2, v200
	v_mfma_f32_32x32x16_bf16 v[82:97], v[176:179], v[130:133], v[82:97]
	ds_read_b128 v[176:179], v180
	ds_read_b128 v[180:183], v180 offset:4096
	ds_read_b128 v[214:217], v198
	v_add_f32_e32 v255, v98, v255
	v_add_f32_e32 v255, v99, v255
	s_waitcnt lgkmcnt(0)
	v_mfma_f32_32x32x16_bf16 v[114:129], v[176:179], v[214:217], v[114:129]
	v_add_f32_e32 v255, v238, v255
	v_add_f32_e32 v255, v239, v255
	v_mfma_f32_32x32x16_bf16 v[82:97], v[180:183], v[214:217], v[82:97]
	v_add_u32_e32 v180, s2, v201
	ds_read_b128 v[176:179], v180
	ds_read_b128 v[180:183], v180 offset:4096
	ds_read_b128 v[214:217], v198 offset:1024
	v_add_f32_e32 v255, v246, v255
	v_add_f32_e32 v255, v247, v255
	s_waitcnt lgkmcnt(0)
; #define SBAR() __builtin_amdgcn_sched_barrier(0)
; __device__ __forceinline__ float max3f(float a, float b, float c) { return __builtin_fmaxf(__builtin_fmaxf(a, b), c); }
; template <bool FIRST, bool MLA>
; __device__ __forceinline__ void partialSM(f32x16& p0, f32x16& p1, f32x16& negm, float& m_reg, float& alpha) {
;   float a = max3f(p0[0], p0[1], p1[0]), b = max3f(p0[2], p0[3], p1[1]); a = max3f(a, p1[2], p1[3]);
; #pragma unroll
;   for (int r = 4; r < 16; r += 4) { a = max3f(a, p0[r], p0[r + 1]); b = max3f(b, p0[r + 2], p0[r + 3]); a = max3f(a, p1[r], p1[r + 1]); b = max3f(b, p1[r + 2], p1[r + 3]); }
;   float pmax = fmaxf(a, b);
;   { auto rr = __builtin_amdgcn_permlane32_swap(__float_as_uint(pmax), __float_as_uint(pmax), false, false);
;     pmax = fmaxf(__uint_as_float(rr[0]), __uint_as_float(rr[1])); }
;   alpha = 1.f;
;   if constexpr (MLA) {
;     if (FIRST) m_reg = pmax;
;     else if (!__builtin_expect(__all(pmax - m_reg <= THR2), 1)) { const float mn = fmaxf(m_reg, pmax); alpha = __builtin_amdgcn_exp2f(m_reg - mn); m_reg = mn; }
; #pragma unroll
;     for (int r = 0; r < 16; ++r) { p0[r] -= m_reg; p1[r] -= m_reg; }
;   } else
;   if (FIRST || __builtin_expect(__any(pmax > THR2), 0)) {
; template <int D0> __device__ __forceinline__ void pv_one(f32x16& od, int vb, bf16x8 pa0, bf16x8 pa1, bf16x8 pa2, bf16x8 pa3) {
;   const s16x4 l0 = tr_read<v_rd_off(D0, 0, 0)>(vb), h0 = tr_read<v_rd_off(D0, 0, 1)>(vb), l1 = tr_read<v_rd_off(D0, 1, 0)>(vb), h1 = tr_read<v_rd_off(D0, 1, 1)>(vb);
;   const s16x4 l2 = tr_read<v_rd_off(D0, 2, 0)>(vb), h2 = tr_read<v_rd_off(D0, 2, 1)>(vb), l3 = tr_read<v_rd_off(D0, 3, 0)>(vb), h3 = tr_read<v_rd_off(D0, 3, 1)>(vb);
;   asm volatile("s_waitcnt lgkmcnt(0)" ::: "memory"); SBAR();
;     ...
;   od = __builtin_amdgcn_mfma_f32_32x32x16_bf16(pa0, PK(l0, h0), od, 0, 0, 0);
;   od = __builtin_amdgcn_mfma_f32_32x32x16_bf16(pa1, PK(l1, h1), od, 0, 0, 0);
;   od = __builtin_amdgcn_mfma_f32_32x32x16_bf16(pa2, PK(l2, h2), od, 0, 0, 0);
;   od = __builtin_amdgcn_mfma_f32_32x32x16_bf16(pa3, PK(l3, h3), od, 0, 0, 0);
;     ...
; }
; __device__ __forceinline__ void pv_d0(f32x16* o, int vb, bf16x8 pa0, bf16x8 pa1, bf16x8 pa2, bf16x8 pa3) {
;   pv_one<0>(o[0], vb, pa0, pa1, pa2, pa3); pv_one<1>(o[1], vb, pa0, pa1, pa2, pa3); pv_one<2>(o[2], vb, pa0, pa1, pa2, pa3); pv_one<3>(o[3], vb, pa0, pa1, pa2, pa3);
	v_mfma_f32_32x32x16_bf16 v[114:129], v[176:179], v[214:217], v[114:129]
	v_add_f32_e32 v255, v249, v255
	v_add_f32_e32 v255, v252, v255
	v_mfma_f32_32x32x16_bf16 v[82:97], v[180:183], v[214:217], v[82:97]
	v_add_u32_e32 v180, s2, v199
	ds_read_b128 v[176:179], v180
	ds_read_b128 v[180:183], v180 offset:4096
	ds_read_b128 v[214:217], v198 offset:2048
	v_add_f32_e32 v255, v253, v255
	v_add_f32_e32 v255, v254, v255
	s_waitcnt lgkmcnt(0)
	v_mfma_f32_32x32x16_bf16 v[114:129], v[176:179], v[214:217], v[114:129]
	v_add_f32_e32 v255, v108, v255
	v_add_f32_e32 v255, v109, v255
	v_mfma_f32_32x32x16_bf16 v[82:97], v[180:183], v[214:217], v[82:97]
	v_add_u32_e32 v180, s2, v202
	ds_read_b128 v[176:179], v180
	ds_read_b128 v[180:183], v180 offset:4096
	ds_read_b128 v[214:217], v198 offset:3072
	v_add_f32_e32 v255, v110, v255
	v_add_f32_e32 v255, v111, v255
	s_waitcnt lgkmcnt(0)
	v_mfma_f32_32x32x16_bf16 v[114:129], v[176:179], v[214:217], v[114:129]
	v_add_f32_e32 v255, v112, v255
	v_add_f32_e32 v255, v113, v255
	v_mfma_f32_32x32x16_bf16 v[82:97], v[180:183], v[214:217], v[82:97]
	v_cvt_pk_bf16_f32 v176, v253, v254
	v_cvt_pk_bf16_f32 v177, v108, v109
	v_cvt_pk_bf16_f32 v178, v110, v111
	v_cvt_pk_bf16_f32 v179, v112, v113
	v_cvt_pk_bf16_f32 v108, v98, v99
	v_cvt_pk_bf16_f32 v109, v238, v239
	v_cvt_pk_bf16_f32 v110, v246, v247
	v_cvt_pk_bf16_f32 v111, v249, v252
	v_mov_b32_e32 v98, v255
	v_add_u32_e32 v112, s11, v197
	ds_read_b64_tr_b16 v[180:181], v112 offset:0
	ds_read_b64_tr_b16 v[182:183], v112 offset:0x800
	ds_read_b64_tr_b16 v[214:215], v112 offset:0x1000
	ds_read_b64_tr_b16 v[216:217], v112 offset:0x1800
	ds_read_b64_tr_b16 v[218:219], v112 offset:0x2000
	ds_read_b64_tr_b16 v[220:221], v112 offset:0x2800
	ds_read_b64_tr_b16 v[222:223], v112 offset:0x3000
	ds_read_b64_tr_b16 v[224:225], v112 offset:0x3800
	s_waitcnt lgkmcnt(0)
	v_mov_b32_e32 v99, v98
	s_nop 1
	v_permlane32_swap_b32_e32 v98, v99
	v_permlane32_swap_b32_e32 v100, v102
	v_permlane32_swap_b32_e32 v176, v178
	v_permlane32_swap_b32_e32 v101, v103
	v_permlane32_swap_b32_e32 v104, v106
	v_permlane32_swap_b32_e32 v105, v107
	v_permlane32_swap_b32_e32 v108, v110
	v_permlane32_swap_b32_e32 v109, v111
	v_permlane32_swap_b32_e32 v177, v179
	v_mfma_f32_32x32x16_bf16 v[50:65], v[100:103], v[180:183], v[50:65]
	ds_read_b64_tr_b16 v[180:181], v112 offset:0x200
	ds_read_b64_tr_b16 v[182:183], v112 offset:0xa00
	v_mfma_f32_32x32x16_bf16 v[50:65], v[104:107], v[214:217], v[50:65]
	ds_read_b64_tr_b16 v[214:215], v112 offset:0x1200
	ds_read_b64_tr_b16 v[216:217], v112 offset:0x1a00
	v_mfma_f32_32x32x16_bf16 v[50:65], v[108:111], v[218:221], v[50:65]
	ds_read_b64_tr_b16 v[218:219], v112 offset:0x2200
	ds_read_b64_tr_b16 v[220:221], v112 offset:0x2a00
	v_mfma_f32_32x32x16_bf16 v[50:65], v[176:179], v[222:225], v[50:65]
	ds_read_b64_tr_b16 v[222:223], v112 offset:0x3200
	ds_read_b64_tr_b16 v[224:225], v112 offset:0x3a00
	s_waitcnt lgkmcnt(6)
	v_mfma_f32_32x32x16_bf16 v[34:49], v[100:103], v[180:183], v[34:49]
	ds_read_b64_tr_b16 v[180:181], v112 offset:0x400
	ds_read_b64_tr_b16 v[182:183], v112 offset:0xc00
	s_waitcnt lgkmcnt(6)
	v_mfma_f32_32x32x16_bf16 v[34:49], v[104:107], v[214:217], v[34:49]
	ds_read_b64_tr_b16 v[214:215], v112 offset:0x1400
	ds_read_b64_tr_b16 v[216:217], v112 offset:0x1c00
	s_waitcnt lgkmcnt(6)
	v_mfma_f32_32x32x16_bf16 v[34:49], v[108:111], v[218:221], v[34:49]
	ds_read_b64_tr_b16 v[218:219], v112 offset:0x2400
	ds_read_b64_tr_b16 v[220:221], v112 offset:0x2c00
	s_waitcnt lgkmcnt(6)
	v_mfma_f32_32x32x16_bf16 v[34:49], v[176:179], v[222:225], v[34:49]
	ds_read_b64_tr_b16 v[222:223], v112 offset:0x3400
	ds_read_b64_tr_b16 v[224:225], v112 offset:0x3c00
	s_waitcnt lgkmcnt(6)
	v_mfma_f32_32x32x16_bf16 v[18:33], v[100:103], v[180:183], v[18:33]
	ds_read_b64_tr_b16 v[180:181], v112 offset:0x600
	ds_read_b64_tr_b16 v[182:183], v112 offset:0xe00
	s_waitcnt lgkmcnt(6)
	v_mfma_f32_32x32x16_bf16 v[18:33], v[104:107], v[214:217], v[18:33]
	ds_read_b64_tr_b16 v[214:215], v112 offset:0x1600
	ds_read_b64_tr_b16 v[216:217], v112 offset:0x1e00
	s_waitcnt lgkmcnt(6)
	v_mfma_f32_32x32x16_bf16 v[18:33], v[108:111], v[218:221], v[18:33]
	ds_read_b64_tr_b16 v[218:219], v112 offset:0x2600
	ds_read_b64_tr_b16 v[220:221], v112 offset:0x2e00
	s_waitcnt lgkmcnt(6)
	v_mfma_f32_32x32x16_bf16 v[18:33], v[176:179], v[222:225], v[18:33]
	ds_read_b64_tr_b16 v[222:223], v112 offset:0x3600
	ds_read_b64_tr_b16 v[224:225], v112 offset:0x3e00
	s_waitcnt lgkmcnt(6)
	v_mfma_f32_32x32x16_bf16 v[2:17], v[100:103], v[180:183], v[2:17]
	v_max_f32_e32 v100, v115, v115
	v_max_f32_e32 v101, v114, v114
	v_max_f32_e32 v100, v101, v100
	v_max3_f32 v101, v116, v117, v83
	v_max3_f32 v100, v100, v82, v84
	v_max3_f32 v100, v100, v85, v118
	v_max3_f32 v101, v101, v120, v121
	s_waitcnt lgkmcnt(4)
	v_mfma_f32_32x32x16_bf16 v[2:17], v[104:107], v[214:217], v[2:17]
	v_max3_f32 v100, v100, v119, v86
	v_max3_f32 v101, v101, v88, v89
	v_max3_f32 v100, v100, v87, v122
	v_max3_f32 v101, v101, v124, v125
	v_max3_f32 v100, v100, v123, v90
	v_max3_f32 v101, v101, v92, v93
	v_max3_f32 v100, v100, v91, v126
	s_waitcnt lgkmcnt(2)
	v_mfma_f32_32x32x16_bf16 v[2:17], v[108:111], v[218:221], v[2:17]
	v_max3_f32 v101, v101, v128, v129
	v_max3_f32 v100, v100, v127, v94
	v_max3_f32 v101, v101, v96, v97
	v_max3_f32 v100, v100, v95, v101
	v_mov_b32_e32 v101, v100
	s_nop 1
	v_permlane32_swap_b32_e32 v100, v101
	s_waitcnt lgkmcnt(0)
	v_mfma_f32_32x32x16_bf16 v[2:17], v[176:179], v[222:225], v[2:17]
	v_max_f32_e32 v101, v101, v101
	v_max_f32_e32 v100, v100, v100
	v_max_f32_e32 v100, v100, v101
	v_cmp_lt_f32_e32 vcc, s40, v100
	v_mov_b32_e32 v176, 1.0
	s_cbranch_vccnz .LBB0_114
	v_cmp_gt_f32_e32 vcc, 1.0, v176
	s_cbranch_vccz .LBB0_111

; __device__ __forceinline__ void finishSM(f32x16& p0, f32x16& p1, float alpha, float& l_reg, bf16x8& pa0, bf16x8& pa1, bf16x8& pa2, bf16x8& pa3) {
; #pragma unroll
;   for (int r = 0; r < 16; ++r) p1[r] = __builtin_amdgcn_exp2f(p1[r]);
;   float ps = 0;
; #pragma unroll
;   for (int r = 0; r < 16; ++r) ps += p0[r];
; #pragma unroll
;   for (int r = 0; r < 16; ++r) ps += p1[r];
;   { auto rr = __builtin_amdgcn_permlane32_swap(__float_as_uint(ps), __float_as_uint(ps), false, false);
;     ps = __uint_as_float(rr[0]) + __uint_as_float(rr[1]); }
;   l_reg = l_reg * alpha + ps;
;     ...
;   PK4(p0, 0, pa0); PK4(p0, 8, pa1); PK4(p1, 0, pa2); PK4(p1, 8, pa3);
; template <bool MLA>
; __device__ __forceinline__ void qkt(f32x16& p0, f32x16& p1, const char* Ks, const char* KRs, const bf16x8* qr, const char* qrl, const f32x16& negm, int r32, int hi) {
; #pragma unroll
;   for (int d0 = 0; d0 < 8; ++d0) { int cb = (d0 * 16 + hi * 8) * 2;
;     bf16x8 b0 = *reinterpret_cast<const bf16x8*>(Ks + KSWZ(r32, cb));
;     bf16x8 b1 = *reinterpret_cast<const bf16x8*>(Ks + KSWZ(32 + r32, cb));
;     if (d0 == 0) { p0 = __builtin_amdgcn_mfma_f32_32x32x16_bf16(b0, qr[0], negm, 0, 0, 0); p1 = __builtin_amdgcn_mfma_f32_32x32x16_bf16(b1, qr[0], negm, 0, 0, 0); }
;     else { p0 = __builtin_amdgcn_mfma_f32_32x32x16_bf16(b0, qr[d0], p0, 0, 0, 0); p1 = __builtin_amdgcn_mfma_f32_32x32x16_bf16(b1, qr[d0], p1, 0, 0, 0); } }
.LBB0_125:
	s_mov_b32 s13, s16
	s_mov_b32 s16, s23
	s_lshl_b32 s8, s17, 14
	s_add_i32 s23, s8, 0
	s_add_i32 s32, s23, s14
	s_lshl_b32 s19, s13, 14
	s_add_i32 s8, s19, 0
	v_add_u32_e32 v98, s8, v199
	ds_read_b128 v[220:223], v98 offset:57344
	ds_read_b128 v[98:101], v98 offset:49152
	v_add_u32_e32 v201, s8, v198
	s_add_u32 vcc_lo, s2, s62
	s_addc_u32 vcc_hi, s3, s63
	s_add_i32 m0, s32, 0xc000
	v_lshl_add_u64 v[250:251], v[168:169], 0, vcc
	global_load_lds_dwordx4 v[250:251], off
	v_exp_f32_e32 v203, v82
	v_add_f32_e32 v82, 0, v217
	v_add_f32_e32 v82, v219, v82
	s_waitcnt lgkmcnt(0)
	v_mfma_f32_32x32x16_bf16 v[114:129], v[98:101], v[158:161], v[66:81]
	v_add_f32_e32 v82, v215, v82
	v_add_f32_e32 v82, v218, v82
	v_add_f32_e32 v82, v214, v82
	v_add_f32_e32 v82, v216, v82
	v_add_f32_e32 v82, v212, v82
	v_add_f32_e32 v82, v213, v82
	v_add_f32_e32 v82, v209, v82
	v_mfma_f32_32x32x16_bf16 v[98:113], v[220:223], v[158:161], v[66:81]
	ds_read_b128 v[220:223], v201 offset:57344
	ds_read_b128 v[224:227], v201 offset:49152
	v_add_u32_e32 v201, s8, v197
	s_add_u32 vcc_lo, s2, 0x1c3c1600
	s_addc_u32 vcc_hi, s3, 0
	s_mov_b32 m0, s32
	v_lshl_add_u64 v[250:251], v[0:1], 0, vcc
	global_load_lds_dwordx4 v[250:251], off
	v_add_f32_e32 v82, v211, v82
	v_add_f32_e32 v82, v208, v82
	v_add_f32_e32 v82, v210, v82
	v_add_f32_e32 v82, v205, v82
	v_add_f32_e32 v82, v207, v82
	s_waitcnt lgkmcnt(0)
	v_mfma_f32_32x32x16_bf16 v[98:113], v[220:223], v[154:157], v[98:113]
	v_add_f32_e32 v82, v204, v82
	v_add_f32_e32 v82, v206, v82
	v_add_f32_e32 v82, v203, v82
	v_exp_f32_e32 v228, v91
	v_exp_f32_e32 v229, v92
	v_exp_f32_e32 v234, v93
	v_exp_f32_e32 v235, v94
	v_mfma_f32_32x32x16_bf16 v[114:129], v[224:227], v[154:157], v[114:129]
	ds_read_b128 v[220:223], v201 offset:57344
	ds_read_b128 v[224:227], v201 offset:49152
	v_add_u32_e32 v201, s8, v196
	s_add_u32 vcc_lo, s2, s62
	s_addc_u32 vcc_hi, s3, s63
	s_add_i32 m0, s32, 0xc400
	v_lshl_add_u64 v[250:251], v[170:171], 0, vcc
	global_load_lds_dwordx4 v[250:251], off
	v_exp_f32_e32 v236, v95
	v_exp_f32_e32 v237, v96
	v_exp_f32_e32 v97, v97
	s_lshl_b32 s24, s16, 14
	s_waitcnt lgkmcnt(0)
	v_mfma_f32_32x32x16_bf16 v[98:113], v[220:223], v[150:153], v[98:113]
	v_mfma_f32_32x32x16_bf16 v[114:129], v[224:227], v[150:153], v[114:129]
	ds_read_b128 v[220:223], v201 offset:57344
	ds_read_b128 v[224:227], v201 offset:49152
	v_add_u32_e32 v201, s8, v195
	s_add_u32 vcc_lo, s2, 0x1c3c1680
	s_addc_u32 vcc_hi, s3, 0
	s_add_i32 m0, s32, 0x400
	v_lshl_add_u64 v[250:251], v[0:1], 0, vcc
	global_load_lds_dwordx4 v[250:251], off
	s_waitcnt lgkmcnt(0)
	v_mfma_f32_32x32x16_bf16 v[98:113], v[220:223], v[146:149], v[98:113]
	v_mfma_f32_32x32x16_bf16 v[114:129], v[224:227], v[146:149], v[114:129]
	ds_read_b128 v[220:223], v201 offset:57344
	ds_read_b128 v[224:227], v201 offset:49152
	v_add_u32_e32 v201, s8, v183
	s_waitcnt lgkmcnt(0)
	v_mfma_f32_32x32x16_bf16 v[98:113], v[220:223], v[142:145], v[98:113]
	v_mfma_f32_32x32x16_bf16 v[114:129], v[224:227], v[142:145], v[114:129]
	ds_read_b128 v[220:223], v201 offset:57344
	ds_read_b128 v[224:227], v201 offset:49152
	v_add_u32_e32 v201, s8, v193
	s_waitcnt lgkmcnt(0)
	v_mfma_f32_32x32x16_bf16 v[98:113], v[220:223], v[138:141], v[98:113]
	v_mfma_f32_32x32x16_bf16 v[114:129], v[224:227], v[138:141], v[114:129]
	ds_read_b128 v[220:223], v201 offset:57344
	ds_read_b128 v[224:227], v201 offset:49152
	v_add_u32_e32 v201, s8, v194
	s_waitcnt lgkmcnt(0)
	v_mfma_f32_32x32x16_bf16 v[98:113], v[220:223], v[134:137], v[98:113]
	v_mfma_f32_32x32x16_bf16 v[114:129], v[224:227], v[134:137], v[114:129]
	ds_read_b128 v[220:223], v201 offset:57344
	ds_read_b128 v[224:227], v201 offset:49152
	s_waitcnt lgkmcnt(0)
	v_mfma_f32_32x32x16_bf16 v[98:113], v[220:223], v[130:133], v[98:113]
	v_exp_f32_e32 v220, v83
	v_exp_f32_e32 v221, v84
	v_exp_f32_e32 v222, v85
	v_exp_f32_e32 v223, v86
	v_add_f32_e32 v82, v220, v82
	v_add_f32_e32 v82, v221, v82
	v_add_f32_e32 v82, v222, v82
	v_mfma_f32_32x32x16_bf16 v[114:129], v[224:227], v[130:133], v[114:129]
	v_exp_f32_e32 v224, v87
	v_exp_f32_e32 v225, v88
	v_exp_f32_e32 v226, v89
	v_exp_f32_e32 v227, v90
	v_add_f32_e32 v82, v223, v82
	v_add_f32_e32 v82, v224, v82
	v_add_f32_e32 v82, v225, v82
	v_add_f32_e32 v82, v226, v82
	v_add_f32_e32 v82, v227, v82
	v_add_f32_e32 v82, v228, v82
	v_add_f32_e32 v82, v229, v82
	v_add_f32_e32 v82, v234, v82
	v_add_f32_e32 v82, v235, v82
	v_add_f32_e32 v82, v236, v82
	v_add_f32_e32 v82, v237, v82
	v_add_f32_e32 v201, v97, v82
	v_cvt_pk_bf16_f32 v82, v217, v219
	v_cvt_pk_bf16_f32 v83, v215, v218
	v_cvt_pk_bf16_f32 v84, v214, v216
	v_cvt_pk_bf16_f32 v85, v212, v213
	v_cvt_pk_bf16_f32 v86, v209, v211
	v_cvt_pk_bf16_f32 v87, v208, v210
	v_cvt_pk_bf16_f32 v88, v205, v207
	v_cvt_pk_bf16_f32 v89, v204, v206
	v_cvt_pk_bf16_f32 v90, v203, v220
	v_cvt_pk_bf16_f32 v91, v221, v222
	v_cvt_pk_bf16_f32 v92, v223, v224
	v_cvt_pk_bf16_f32 v93, v225, v226
	v_cvt_pk_bf16_f32 v94, v227, v228
	v_cvt_pk_bf16_f32 v95, v229, v234
	v_cvt_pk_bf16_f32 v96, v235, v236
	v_cvt_pk_bf16_f32 v97, v237, v97
	v_add_u32_e32 v203, s24, v182
	ds_read_b64_tr_b16 v[204:205], v203 offset:0
	ds_read_b64_tr_b16 v[206:207], v203 offset:0x800
	ds_read_b64_tr_b16 v[208:209], v203 offset:0x1000
	ds_read_b64_tr_b16 v[210:211], v203 offset:0x1800
	ds_read_b64_tr_b16 v[212:213], v203 offset:0x2000
	ds_read_b64_tr_b16 v[214:215], v203 offset:0x2800
	ds_read_b64_tr_b16 v[216:217], v203 offset:0x3000
	ds_read_b64_tr_b16 v[218:219], v203 offset:0x3800
	s_waitcnt lgkmcnt(0)
; #define SBAR() __builtin_amdgcn_sched_barrier(0)
; __device__ __forceinline__ float max3f(float a, float b, float c) { return __builtin_fmaxf(__builtin_fmaxf(a, b), c); }
; template <bool FIRST, bool MLA>
; __device__ __forceinline__ void partialSM(f32x16& p0, f32x16& p1, f32x16& negm, float& m_reg, float& alpha) {
;   float a = max3f(p0[0], p0[1], p1[0]), b = max3f(p0[2], p0[3], p1[1]); a = max3f(a, p1[2], p1[3]);
; #pragma unroll
;   for (int r = 4; r < 16; r += 4) { a = max3f(a, p0[r], p0[r + 1]); b = max3f(b, p0[r + 2], p0[r + 3]); a = max3f(a, p1[r], p1[r + 1]); b = max3f(b, p1[r + 2], p1[r + 3]); }
;   float pmax = fmaxf(a, b);
;   { auto rr = __builtin_amdgcn_permlane32_swap(__float_as_uint(pmax), __float_as_uint(pmax), false, false);
;     pmax = fmaxf(__uint_as_float(rr[0]), __uint_as_float(rr[1])); }
;   alpha = 1.f;
;   if constexpr (MLA) {
;     if (FIRST) m_reg = pmax;
;     else if (!__builtin_expect(__all(pmax - m_reg <= THR2), 1)) { const float mn = fmaxf(m_reg, pmax); alpha = __builtin_amdgcn_exp2f(m_reg - mn); m_reg = mn; }
; #pragma unroll
;     for (int r = 0; r < 16; ++r) { p0[r] -= m_reg; p1[r] -= m_reg; }
;   } else
;   if (FIRST || __builtin_expect(__any(pmax > THR2), 0)) {
; template <int D0> __device__ __forceinline__ void pv_one(f32x16& od, int vb, bf16x8 pa0, bf16x8 pa1, bf16x8 pa2, bf16x8 pa3) {
;   const s16x4 l0 = tr_read<v_rd_off(D0, 0, 0)>(vb), h0 = tr_read<v_rd_off(D0, 0, 1)>(vb), l1 = tr_read<v_rd_off(D0, 1, 0)>(vb), h1 = tr_read<v_rd_off(D0, 1, 1)>(vb);
;   const s16x4 l2 = tr_read<v_rd_off(D0, 2, 0)>(vb), h2 = tr_read<v_rd_off(D0, 2, 1)>(vb), l3 = tr_read<v_rd_off(D0, 3, 0)>(vb), h3 = tr_read<v_rd_off(D0, 3, 1)>(vb);
;   asm volatile("s_waitcnt lgkmcnt(0)" ::: "memory"); SBAR();
;     ...
;   od = __builtin_amdgcn_mfma_f32_32x32x16_bf16(pa0, PK(l0, h0), od, 0, 0, 0);
;   od = __builtin_amdgcn_mfma_f32_32x32x16_bf16(pa1, PK(l1, h1), od, 0, 0, 0);
;   od = __builtin_amdgcn_mfma_f32_32x32x16_bf16(pa2, PK(l2, h2), od, 0, 0, 0);
;   od = __builtin_amdgcn_mfma_f32_32x32x16_bf16(pa3, PK(l3, h3), od, 0, 0, 0);
;     ...
; }
; __device__ __forceinline__ void pv_d0(f32x16* o, int vb, bf16x8 pa0, bf16x8 pa1, bf16x8 pa2, bf16x8 pa3) {
;   pv_one<0>(o[0], vb, pa0, pa1, pa2, pa3); pv_one<1>(o[1], vb, pa0, pa1, pa2, pa3); pv_one<2>(o[2], vb, pa0, pa1, pa2, pa3); pv_one<3>(o[3], vb, pa0, pa1, pa2, pa3);
	v_mov_b32_e32 v202, v201
	s_nop 1
	v_permlane32_swap_b32_e32 v201, v202
	v_permlane32_swap_b32_e32 v82, v84
	v_permlane32_swap_b32_e32 v83, v85
	v_permlane32_swap_b32_e32 v86, v88
	v_permlane32_swap_b32_e32 v87, v89
	v_permlane32_swap_b32_e32 v90, v92
	v_permlane32_swap_b32_e32 v91, v93
	v_permlane32_swap_b32_e32 v94, v96
	v_permlane32_swap_b32_e32 v95, v97
	v_mfma_f32_32x32x16_bf16 v[2:17], v[82:85], v[204:207], v[2:17]
	ds_read_b64_tr_b16 v[204:205], v203 offset:0x200
	ds_read_b64_tr_b16 v[206:207], v203 offset:0xa00
	v_mfma_f32_32x32x16_bf16 v[2:17], v[86:89], v[208:211], v[2:17]
	ds_read_b64_tr_b16 v[208:209], v203 offset:0x1200
	ds_read_b64_tr_b16 v[210:211], v203 offset:0x1a00
	v_mfma_f32_32x32x16_bf16 v[2:17], v[90:93], v[212:215], v[2:17]
	ds_read_b64_tr_b16 v[212:213], v203 offset:0x2200
	ds_read_b64_tr_b16 v[214:215], v203 offset:0x2a00
	v_mfma_f32_32x32x16_bf16 v[2:17], v[94:97], v[216:219], v[2:17]
	ds_read_b64_tr_b16 v[216:217], v203 offset:0x3200
	ds_read_b64_tr_b16 v[218:219], v203 offset:0x3a00
	s_waitcnt lgkmcnt(6)
	v_mfma_f32_32x32x16_bf16 v[50:65], v[82:85], v[204:207], v[50:65]
	ds_read_b64_tr_b16 v[204:205], v203 offset:0x400
	ds_read_b64_tr_b16 v[206:207], v203 offset:0xc00
	s_waitcnt lgkmcnt(6)
	v_mfma_f32_32x32x16_bf16 v[50:65], v[86:89], v[208:211], v[50:65]
	ds_read_b64_tr_b16 v[208:209], v203 offset:0x1400
	ds_read_b64_tr_b16 v[210:211], v203 offset:0x1c00
	s_waitcnt lgkmcnt(6)
	v_mfma_f32_32x32x16_bf16 v[50:65], v[90:93], v[212:215], v[50:65]
	ds_read_b64_tr_b16 v[212:213], v203 offset:0x2400
	ds_read_b64_tr_b16 v[214:215], v203 offset:0x2c00
	s_waitcnt lgkmcnt(6)
	v_mfma_f32_32x32x16_bf16 v[50:65], v[94:97], v[216:219], v[50:65]
	ds_read_b64_tr_b16 v[216:217], v203 offset:0x3400
	ds_read_b64_tr_b16 v[218:219], v203 offset:0x3c00
	s_waitcnt lgkmcnt(6)
	v_mfma_f32_32x32x16_bf16 v[34:49], v[82:85], v[204:207], v[34:49]
	ds_read_b64_tr_b16 v[204:205], v203 offset:0x600
	ds_read_b64_tr_b16 v[206:207], v203 offset:0xe00
	s_waitcnt lgkmcnt(6)
	v_mfma_f32_32x32x16_bf16 v[34:49], v[86:89], v[208:211], v[34:49]
	ds_read_b64_tr_b16 v[208:209], v203 offset:0x1600
	ds_read_b64_tr_b16 v[210:211], v203 offset:0x1e00
	s_waitcnt lgkmcnt(6)
	v_mfma_f32_32x32x16_bf16 v[34:49], v[90:93], v[212:215], v[34:49]
	ds_read_b64_tr_b16 v[212:213], v203 offset:0x2600
	ds_read_b64_tr_b16 v[214:215], v203 offset:0x2e00
	s_waitcnt lgkmcnt(6)
	v_mfma_f32_32x32x16_bf16 v[34:49], v[94:97], v[216:219], v[34:49]
	ds_read_b64_tr_b16 v[216:217], v203 offset:0x3600
	ds_read_b64_tr_b16 v[218:219], v203 offset:0x3e00
	s_waitcnt lgkmcnt(6)
	v_mfma_f32_32x32x16_bf16 v[18:33], v[82:85], v[204:207], v[18:33]
	v_max_f32_e32 v82, v115, v115
	v_max_f32_e32 v83, v114, v114
	v_max_f32_e32 v82, v83, v82
	v_max3_f32 v83, v116, v117, v99
	v_max3_f32 v82, v82, v98, v100
	v_max3_f32 v82, v82, v101, v118
	v_max3_f32 v83, v83, v120, v121
	s_waitcnt lgkmcnt(4)
	v_mfma_f32_32x32x16_bf16 v[18:33], v[86:89], v[208:211], v[18:33]
	v_max3_f32 v82, v82, v119, v102
	v_max3_f32 v83, v83, v104, v105
	v_max3_f32 v82, v82, v103, v122
	v_max3_f32 v83, v83, v124, v125
	v_max3_f32 v82, v82, v123, v106
	v_max3_f32 v83, v83, v108, v109
	v_max3_f32 v82, v82, v107, v126
	s_waitcnt lgkmcnt(2)
	v_mfma_f32_32x32x16_bf16 v[18:33], v[90:93], v[212:215], v[18:33]
	v_max3_f32 v83, v83, v128, v129
	v_max3_f32 v82, v82, v127, v110
	v_max3_f32 v83, v83, v112, v113
	v_max3_f32 v82, v82, v111, v83
	v_mov_b32_e32 v83, v82
	s_nop 1
	v_permlane32_swap_b32_e32 v82, v83
	s_waitcnt lgkmcnt(0)
	v_mfma_f32_32x32x16_bf16 v[18:33], v[94:97], v[216:219], v[18:33]
	v_max_f32_e32 v83, v83, v83
	v_max_f32_e32 v82, v82, v82
	v_max_f32_e32 v82, v82, v83
	v_cmp_lt_f32_e32 vcc, s40, v82
	s_cbranch_vccnz .LBB0_137
	v_mov_b32_e32 v203, 1.0
	v_cmp_gt_f32_e32 vcc, 1.0, v203
	s_cbranch_vccz .LBB0_130

; #define SBAR() __builtin_amdgcn_sched_barrier(0)
; #define WAIT_BAR() do { asm volatile("s_waitcnt vmcnt(0)" ::: "memory"); __syncthreads(); } while (0)
; #define RESC(a) do { if (__any((a) < 1.f)) { if (hi == 0) al_l[r32] = (a); asm volatile("s_waitcnt lgkmcnt(0)" ::: "memory"); \
;     _Pragma("unroll") for (int d = 0; d < 4; ++d) _Pragma("unroll") for (int r = 0; r < 16; ++r) o[d][r] *= al_l[crow(r, hi)]; } } while (0)
; #define ROT() do { const int t_ = s_prev; s_prev = s_cur; s_cur = s_next; s_next = t_; } while (0)
; template <bool MLA>
; __device__ __forceinline__ void qkt(f32x16& p0, f32x16& p1, const char* Ks, const char* KRs, const bf16x8* qr, const char* qrl, const f32x16& negm, int r32, int hi) {
; #pragma unroll
;   for (int d0 = 0; d0 < 8; ++d0) { int cb = (d0 * 16 + hi * 8) * 2;
;     bf16x8 b0 = *reinterpret_cast<const bf16x8*>(Ks + KSWZ(r32, cb));
;     bf16x8 b1 = *reinterpret_cast<const bf16x8*>(Ks + KSWZ(32 + r32, cb));
;     if (d0 == 0) { p0 = __builtin_amdgcn_mfma_f32_32x32x16_bf16(b0, qr[0], negm, 0, 0, 0); p1 = __builtin_amdgcn_mfma_f32_32x32x16_bf16(b1, qr[0], negm, 0, 0, 0); }
;     else { p0 = __builtin_amdgcn_mfma_f32_32x32x16_bf16(b0, qr[d0], p0, 0, 0, 0); p1 = __builtin_amdgcn_mfma_f32_32x32x16_bf16(b1, qr[d0], p1, 0, 0, 0); } }
; template <bool MLA> ...
;     ...
;     RESC(alB); WAIT_BAR(); ROT();
;     SBAR(); DMA_TILE(j + 2, s_next); SBAR();
;     qkt<MLA>(pA0, pA1, K_lds + s_cur * SHM_K, KR_lds + s_cur * SHM_KR, qr, qrl, negm, r32, hi);
;     finishSM(pB0, pB1, alB, l_reg, pa0, pa1, pa2, pa3);
;     pv_d0(o, vb0 + s_prev * SHM_V, pa0, pa1, pa2, pa3); partialSM<false, false>(pA0, pA1, negm, m_reg, alA);
;     RESC(alA); WAIT_BAR(); ROT();
.LBB0_130:
	s_waitcnt vmcnt(0)
	v_exp_f32_e32 v208, v114
	v_exp_f32_e32 v209, v115
	v_exp_f32_e32 v210, v116
	v_exp_f32_e32 v211, v117
	v_exp_f32_e32 v212, v118
	v_exp_f32_e32 v213, v119
	v_exp_f32_e32 v214, v120
	v_exp_f32_e32 v215, v121
	v_exp_f32_e32 v216, v122
	v_exp_f32_e32 v217, v123
	v_exp_f32_e32 v218, v124
	v_exp_f32_e32 v219, v125
	v_exp_f32_e32 v220, v126
	v_exp_f32_e32 v221, v127
	v_exp_f32_e32 v222, v128
	v_exp_f32_e32 v223, v129
	s_waitcnt vmcnt(0)
	s_barrier
	s_add_i32 s24, s15, s24
	v_add_u32_e32 v82, s23, v199
	ds_read_b128 v[172:175], v82 offset:57344
	ds_read_b128 v[82:85], v82 offset:49152
	v_add_u32_e32 v176, s23, v198
	s_add_u32 vcc_lo, s2, s74
	s_addc_u32 vcc_hi, s3, s75
	s_add_i32 m0, s24, 0xc000
	v_lshl_add_u64 v[250:251], v[168:169], 0, vcc
	global_load_lds_dwordx4 v[250:251], off
	v_exp_f32_e32 v177, v103
	v_exp_f32_e32 v224, v108
	v_exp_f32_e32 v225, v109
	s_waitcnt lgkmcnt(0)
	v_mfma_f32_32x32x16_bf16 v[114:129], v[82:85], v[158:161], v[66:81]
	v_exp_f32_e32 v226, v110
	v_exp_f32_e32 v227, v111
	v_exp_f32_e32 v112, v112
	v_exp_f32_e32 v113, v113
	v_mfma_f32_32x32x16_bf16 v[82:97], v[172:175], v[158:161], v[66:81]
	ds_read_b128 v[172:175], v176 offset:57344
	ds_read_b128 v[204:207], v176 offset:49152
	v_add_u32_e32 v176, s23, v197
	s_add_u32 vcc_lo, s2, 0x1c421600
	s_addc_u32 vcc_hi, s3, 0
	s_mov_b32 m0, s24
	v_lshl_add_u64 v[250:251], v[0:1], 0, vcc
	global_load_lds_dwordx4 v[250:251], off
	s_waitcnt lgkmcnt(0)
	v_mfma_f32_32x32x16_bf16 v[82:97], v[172:175], v[154:157], v[82:97]
	v_mfma_f32_32x32x16_bf16 v[114:129], v[204:207], v[154:157], v[114:129]
	ds_read_b128 v[172:175], v176 offset:57344
	ds_read_b128 v[204:207], v176 offset:49152
	v_add_u32_e32 v176, s23, v196
	s_add_u32 vcc_lo, s2, s74
	s_addc_u32 vcc_hi, s3, s75
	s_add_i32 m0, s24, 0xc400
	v_lshl_add_u64 v[250:251], v[170:171], 0, vcc
	global_load_lds_dwordx4 v[250:251], off
	s_waitcnt lgkmcnt(0)
	v_mfma_f32_32x32x16_bf16 v[82:97], v[172:175], v[150:153], v[82:97]
	v_mfma_f32_32x32x16_bf16 v[114:129], v[204:207], v[150:153], v[114:129]
	ds_read_b128 v[172:175], v176 offset:57344
	ds_read_b128 v[204:207], v176 offset:49152
	v_add_u32_e32 v176, s23, v195
	s_add_u32 vcc_lo, s2, 0x1c421680
	s_addc_u32 vcc_hi, s3, 0
	s_add_i32 m0, s24, 0x400
	v_lshl_add_u64 v[250:251], v[0:1], 0, vcc
	global_load_lds_dwordx4 v[250:251], off
	s_waitcnt lgkmcnt(0)
	v_mfma_f32_32x32x16_bf16 v[82:97], v[172:175], v[146:149], v[82:97]
	v_mfma_f32_32x32x16_bf16 v[114:129], v[204:207], v[146:149], v[114:129]
	ds_read_b128 v[172:175], v176 offset:57344
	ds_read_b128 v[204:207], v176 offset:49152
	v_add_u32_e32 v176, s23, v183
	s_waitcnt lgkmcnt(0)
	v_mfma_f32_32x32x16_bf16 v[82:97], v[172:175], v[142:145], v[82:97]
	v_mfma_f32_32x32x16_bf16 v[114:129], v[204:207], v[142:145], v[114:129]
	ds_read_b128 v[172:175], v176 offset:57344
	ds_read_b128 v[204:207], v176 offset:49152
	v_add_u32_e32 v176, s23, v193
	s_waitcnt lgkmcnt(0)
	v_mfma_f32_32x32x16_bf16 v[82:97], v[172:175], v[138:141], v[82:97]
	v_mfma_f32_32x32x16_bf16 v[114:129], v[204:207], v[138:141], v[114:129]
	ds_read_b128 v[172:175], v176 offset:57344
	ds_read_b128 v[204:207], v176 offset:49152
	v_add_u32_e32 v176, s23, v194
	s_waitcnt lgkmcnt(0)
	v_mfma_f32_32x32x16_bf16 v[82:97], v[172:175], v[134:137], v[82:97]
	v_mfma_f32_32x32x16_bf16 v[114:129], v[204:207], v[134:137], v[114:129]
	ds_read_b128 v[172:175], v176 offset:57344
	ds_read_b128 v[204:207], v176 offset:49152
	v_exp_f32_e32 v176, v102
	s_waitcnt lgkmcnt(0)
	v_mfma_f32_32x32x16_bf16 v[82:97], v[172:175], v[130:133], v[82:97]
	v_exp_f32_e32 v172, v98
	v_add_f32_e32 v98, 0, v208
	v_add_f32_e32 v98, v209, v98
	v_add_f32_e32 v98, v210, v98
	v_add_f32_e32 v98, v211, v98
	v_add_f32_e32 v98, v212, v98
	v_add_f32_e32 v98, v213, v98
	v_add_f32_e32 v98, v214, v98
	v_add_f32_e32 v98, v215, v98
	v_add_f32_e32 v98, v216, v98
	v_add_f32_e32 v98, v217, v98
	v_add_f32_e32 v98, v218, v98
	v_add_f32_e32 v98, v219, v98
	v_add_f32_e32 v98, v220, v98
	v_exp_f32_e32 v173, v99
	v_add_f32_e32 v98, v221, v98
	v_exp_f32_e32 v174, v100
	v_add_f32_e32 v98, v222, v98
	v_exp_f32_e32 v175, v101
	v_add_f32_e32 v98, v223, v98
	v_add_f32_e32 v98, v172, v98
	v_add_f32_e32 v98, v173, v98
	v_mfma_f32_32x32x16_bf16 v[114:129], v[204:207], v[130:133], v[114:129]
	v_exp_f32_e32 v204, v104
	v_add_f32_e32 v98, v174, v98
	v_exp_f32_e32 v205, v105
	v_add_f32_e32 v98, v175, v98
	v_exp_f32_e32 v206, v106
	v_add_f32_e32 v98, v176, v98
	v_exp_f32_e32 v207, v107
	v_add_f32_e32 v98, v177, v98
	v_add_f32_e32 v98, v204, v98
	v_add_f32_e32 v98, v205, v98
	v_add_f32_e32 v98, v206, v98
	v_add_f32_e32 v98, v207, v98
	v_add_f32_e32 v98, v224, v98
	v_add_f32_e32 v98, v225, v98
	v_add_f32_e32 v98, v226, v98
	v_add_f32_e32 v98, v227, v98
	v_add_f32_e32 v98, v112, v98
	v_cvt_pk_bf16_f32 v100, v208, v209
	v_cvt_pk_bf16_f32 v101, v210, v211
	v_cvt_pk_bf16_f32 v102, v212, v213
	v_cvt_pk_bf16_f32 v103, v214, v215
	v_cvt_pk_bf16_f32 v104, v216, v217
	v_cvt_pk_bf16_f32 v105, v218, v219
	v_cvt_pk_bf16_f32 v106, v220, v221
	v_cvt_pk_bf16_f32 v107, v222, v223
	v_cvt_pk_bf16_f32 v108, v172, v173
	v_cvt_pk_bf16_f32 v109, v174, v175
	v_cvt_pk_bf16_f32 v110, v176, v177
	v_cvt_pk_bf16_f32 v111, v204, v205
	v_cvt_pk_bf16_f32 v172, v206, v207
	v_cvt_pk_bf16_f32 v173, v224, v225
	v_cvt_pk_bf16_f32 v174, v226, v227
	v_cvt_pk_bf16_f32 v175, v112, v113
	v_add_u32_e32 v112, s19, v182
	ds_read_b64_tr_b16 v[204:205], v112 offset:0
	ds_read_b64_tr_b16 v[206:207], v112 offset:0x800
	ds_read_b64_tr_b16 v[208:209], v112 offset:0x1000
	ds_read_b64_tr_b16 v[210:211], v112 offset:0x1800
	ds_read_b64_tr_b16 v[212:213], v112 offset:0x2000
	ds_read_b64_tr_b16 v[214:215], v112 offset:0x2800
	ds_read_b64_tr_b16 v[216:217], v112 offset:0x3000
	ds_read_b64_tr_b16 v[218:219], v112 offset:0x3800
	v_add_f32_e32 v98, v113, v98
	s_waitcnt lgkmcnt(0)
; #define SBAR() __builtin_amdgcn_sched_barrier(0)
; __device__ __forceinline__ float max3f(float a, float b, float c) { return __builtin_fmaxf(__builtin_fmaxf(a, b), c); }
; template <bool FIRST, bool MLA>
; __device__ __forceinline__ void partialSM(f32x16& p0, f32x16& p1, f32x16& negm, float& m_reg, float& alpha) {
;   float a = max3f(p0[0], p0[1], p1[0]), b = max3f(p0[2], p0[3], p1[1]); a = max3f(a, p1[2], p1[3]);
; #pragma unroll
;   for (int r = 4; r < 16; r += 4) { a = max3f(a, p0[r], p0[r + 1]); b = max3f(b, p0[r + 2], p0[r + 3]); a = max3f(a, p1[r], p1[r + 1]); b = max3f(b, p1[r + 2], p1[r + 3]); }
;   float pmax = fmaxf(a, b);
;   { auto rr = __builtin_amdgcn_permlane32_swap(__float_as_uint(pmax), __float_as_uint(pmax), false, false);
;     pmax = fmaxf(__uint_as_float(rr[0]), __uint_as_float(rr[1])); }
;   alpha = 1.f;
;   if constexpr (MLA) {
;     if (FIRST) m_reg = pmax;
;     else if (!__builtin_expect(__all(pmax - m_reg <= THR2), 1)) { const float mn = fmaxf(m_reg, pmax); alpha = __builtin_amdgcn_exp2f(m_reg - mn); m_reg = mn; }
; #pragma unroll
;     for (int r = 0; r < 16; ++r) { p0[r] -= m_reg; p1[r] -= m_reg; }
;   } else
;   if (FIRST || __builtin_expect(__any(pmax > THR2), 0)) {
; template <int D0> __device__ __forceinline__ void pv_one(f32x16& od, int vb, bf16x8 pa0, bf16x8 pa1, bf16x8 pa2, bf16x8 pa3) {
;   const s16x4 l0 = tr_read<v_rd_off(D0, 0, 0)>(vb), h0 = tr_read<v_rd_off(D0, 0, 1)>(vb), l1 = tr_read<v_rd_off(D0, 1, 0)>(vb), h1 = tr_read<v_rd_off(D0, 1, 1)>(vb);
;   const s16x4 l2 = tr_read<v_rd_off(D0, 2, 0)>(vb), h2 = tr_read<v_rd_off(D0, 2, 1)>(vb), l3 = tr_read<v_rd_off(D0, 3, 0)>(vb), h3 = tr_read<v_rd_off(D0, 3, 1)>(vb);
;   asm volatile("s_waitcnt lgkmcnt(0)" ::: "memory"); SBAR();
;     ...
;   od = __builtin_amdgcn_mfma_f32_32x32x16_bf16(pa0, PK(l0, h0), od, 0, 0, 0);
;   od = __builtin_amdgcn_mfma_f32_32x32x16_bf16(pa1, PK(l1, h1), od, 0, 0, 0);
;   od = __builtin_amdgcn_mfma_f32_32x32x16_bf16(pa2, PK(l2, h2), od, 0, 0, 0);
;   od = __builtin_amdgcn_mfma_f32_32x32x16_bf16(pa3, PK(l3, h3), od, 0, 0, 0);
;     ...
; }
; __device__ __forceinline__ void pv_d0(f32x16* o, int vb, bf16x8 pa0, bf16x8 pa1, bf16x8 pa2, bf16x8 pa3) {
;   pv_one<0>(o[0], vb, pa0, pa1, pa2, pa3); pv_one<1>(o[1], vb, pa0, pa1, pa2, pa3); pv_one<2>(o[2], vb, pa0, pa1, pa2, pa3); pv_one<3>(o[3], vb, pa0, pa1, pa2, pa3);
	v_mov_b32_e32 v99, v98
	s_nop 1
	v_permlane32_swap_b32_e32 v98, v99
	v_permlane32_swap_b32_e32 v100, v102
	v_permlane32_swap_b32_e32 v172, v174
	v_permlane32_swap_b32_e32 v101, v103
	v_permlane32_swap_b32_e32 v104, v106
	v_permlane32_swap_b32_e32 v105, v107
	v_permlane32_swap_b32_e32 v108, v110
	v_permlane32_swap_b32_e32 v109, v111
	v_permlane32_swap_b32_e32 v173, v175
	v_mfma_f32_32x32x16_bf16 v[2:17], v[100:103], v[204:207], v[2:17]
	ds_read_b64_tr_b16 v[204:205], v112 offset:0x200
	ds_read_b64_tr_b16 v[206:207], v112 offset:0xa00
	v_mfma_f32_32x32x16_bf16 v[2:17], v[104:107], v[208:211], v[2:17]
	ds_read_b64_tr_b16 v[208:209], v112 offset:0x1200
	ds_read_b64_tr_b16 v[210:211], v112 offset:0x1a00
	v_mfma_f32_32x32x16_bf16 v[2:17], v[108:111], v[212:215], v[2:17]
	ds_read_b64_tr_b16 v[212:213], v112 offset:0x2200
	ds_read_b64_tr_b16 v[214:215], v112 offset:0x2a00
	v_mfma_f32_32x32x16_bf16 v[2:17], v[172:175], v[216:219], v[2:17]
	ds_read_b64_tr_b16 v[216:217], v112 offset:0x3200
	ds_read_b64_tr_b16 v[218:219], v112 offset:0x3a00
	s_waitcnt lgkmcnt(6)
	v_mfma_f32_32x32x16_bf16 v[50:65], v[100:103], v[204:207], v[50:65]
	ds_read_b64_tr_b16 v[204:205], v112 offset:0x400
	ds_read_b64_tr_b16 v[206:207], v112 offset:0xc00
	s_waitcnt lgkmcnt(6)
	v_mfma_f32_32x32x16_bf16 v[50:65], v[104:107], v[208:211], v[50:65]
	ds_read_b64_tr_b16 v[208:209], v112 offset:0x1400
	ds_read_b64_tr_b16 v[210:211], v112 offset:0x1c00
	s_waitcnt lgkmcnt(6)
	v_mfma_f32_32x32x16_bf16 v[50:65], v[108:111], v[212:215], v[50:65]
	ds_read_b64_tr_b16 v[212:213], v112 offset:0x2400
	ds_read_b64_tr_b16 v[214:215], v112 offset:0x2c00
	s_waitcnt lgkmcnt(6)
	v_mfma_f32_32x32x16_bf16 v[50:65], v[172:175], v[216:219], v[50:65]
	ds_read_b64_tr_b16 v[216:217], v112 offset:0x3400
	ds_read_b64_tr_b16 v[218:219], v112 offset:0x3c00
	s_waitcnt lgkmcnt(6)
	v_mfma_f32_32x32x16_bf16 v[34:49], v[100:103], v[204:207], v[34:49]
	ds_read_b64_tr_b16 v[204:205], v112 offset:0x600
	ds_read_b64_tr_b16 v[206:207], v112 offset:0xe00
	s_waitcnt lgkmcnt(6)
	v_mfma_f32_32x32x16_bf16 v[34:49], v[104:107], v[208:211], v[34:49]
	ds_read_b64_tr_b16 v[208:209], v112 offset:0x1600
	ds_read_b64_tr_b16 v[210:211], v112 offset:0x1e00
	s_waitcnt lgkmcnt(6)
	v_mfma_f32_32x32x16_bf16 v[34:49], v[108:111], v[212:215], v[34:49]
	ds_read_b64_tr_b16 v[212:213], v112 offset:0x2600
	ds_read_b64_tr_b16 v[214:215], v112 offset:0x2e00
	s_waitcnt lgkmcnt(6)
	v_mfma_f32_32x32x16_bf16 v[34:49], v[172:175], v[216:219], v[34:49]
	ds_read_b64_tr_b16 v[216:217], v112 offset:0x3600
	ds_read_b64_tr_b16 v[218:219], v112 offset:0x3e00
	s_waitcnt lgkmcnt(6)
	v_mfma_f32_32x32x16_bf16 v[18:33], v[100:103], v[204:207], v[18:33]
	v_max_f32_e32 v100, v115, v115
	v_max_f32_e32 v101, v114, v114
	v_max_f32_e32 v100, v101, v100
	v_max3_f32 v101, v116, v117, v83
	v_max3_f32 v100, v100, v82, v84
	v_max3_f32 v100, v100, v85, v118
	v_max3_f32 v101, v101, v120, v121
	s_waitcnt lgkmcnt(4)
	v_mfma_f32_32x32x16_bf16 v[18:33], v[104:107], v[208:211], v[18:33]
	v_max3_f32 v100, v100, v119, v86
	v_max3_f32 v101, v101, v88, v89
	v_max3_f32 v100, v100, v87, v122
	v_max3_f32 v101, v101, v124, v125
	v_max3_f32 v100, v100, v123, v90
	v_max3_f32 v101, v101, v92, v93
	v_max3_f32 v100, v100, v91, v126
	s_waitcnt lgkmcnt(2)
	v_mfma_f32_32x32x16_bf16 v[18:33], v[108:111], v[212:215], v[18:33]
	v_max3_f32 v101, v101, v128, v129
	v_max3_f32 v100, v100, v127, v94
	v_max3_f32 v101, v101, v96, v97
	v_max3_f32 v100, v100, v95, v101
	v_mov_b32_e32 v101, v100
	s_nop 1
	v_permlane32_swap_b32_e32 v100, v101
	s_waitcnt lgkmcnt(0)
	v_mfma_f32_32x32x16_bf16 v[18:33], v[172:175], v[216:219], v[18:33]
	v_max_f32_e32 v101, v101, v101
	v_max_f32_e32 v100, v100, v100
	v_max_f32_e32 v100, v100, v101
	v_cmp_lt_f32_e32 vcc, s40, v100
	v_mov_b32_e32 v172, 1.0
	s_cbranch_vccnz .LBB0_138
	v_cmp_gt_f32_e32 vcc, 1.0, v172
	s_cbranch_vccz .LBB0_135
